# G2->LN1, LN1->G3 and PEER->G1 seams use an XCD-local release (no cross-XCD stage, no L2 write-back) when a run-time census confirms every quarter sits on one XCD; plus B attention loop reschedule
# speedup vs baseline: 1.1129x; 1.0224x over previous
.LBB0_2:
	s_or_b64 exec, exec, s[10:11]
	s_and_b32 s3, s2, 1
	s_waitcnt lgkmcnt(0)
	s_add_u32 s10, s74, 0x18928500
	s_addc_u32 s11, s75, 0
	s_lshl_b32 s76, s3, 14
	v_writelane_b32 v253, s3, 0
	s_add_u32 s3, s10, s76
	s_load_dword s33, s[0:1], 0xe0
	s_addc_u32 s86, s11, 0
	s_add_u32 s4, s3, 0x4000
	s_addc_u32 s5, s86, 0
	v_writelane_b32 v253, s4, 1
	s_waitcnt lgkmcnt(0)
	s_barrier
	v_writelane_b32 v253, s5, 2
	s_getreg_b32 s16, hwreg(HW_REG_XCC_ID, 0, 4)
	s_and_b32 s98, s2, 7
	s_lshl_b32 s98, s98, 2
	s_and_b32 s99, s16, 15
	s_lshl_b32 s99, 1, s99
	s_and_saveexec_b64 s[100:101], s[14:15]
	s_cbranch_execz .Llayout_posted
	v_mov_b32_e32 v2, s98
	v_mov_b32_e32 v3, s99
	s_add_u32 s98, s10, 0xc100
	s_addc_u32 s99, s11, 0
	global_atomic_or v2, v3, s[98:99]
.Llayout_posted:
	s_or_b64 exec, exec, s[100:101]
	s_and_saveexec_b64 s[4:5], vcc
	s_xor_b64 s[4:5], exec, s[4:5]
	s_getreg_b32 s6, hwreg(HW_REG_XCC_ID, 0, 4)
	s_andn2_saveexec_b64 s[4:5], s[4:5]
	s_cbranch_execz .LBB0_10
	s_mov_b64 s[12:13], exec
	v_mbcnt_lo_u32_b32 v1, s12, 0
	v_mbcnt_hi_u32_b32 v1, s13, v1
	v_cmp_eq_u32_e32 vcc, 0, v1
	s_and_saveexec_b64 s[6:7], vcc
	s_cbranch_execz .LBB0_7
	s_lshl_b32 s16, s16, 8
	s_and_b32 s16, s16, 0xf00
	s_bcnt1_i32_b64 s12, s[12:13]
	v_mov_b32_e32 v1, s16
	v_mov_b32_e32 v2, s12
	global_atomic_add v1, v2, s[10:11] offset:1024

.LBB0_291:
	s_add_u32 s98, s74, 0x18934600
	s_addc_u32 s99, s75, 0
	v_and_b32_e32 v0, 7, v160
	v_lshlrev_b32_e32 v0, 2, v0
	global_load_dword v0, v0, s[98:99] sc1
	s_waitcnt vmcnt(0)
	v_bcnt_u32_b32 v0, v0, 0
	v_cmp_ne_u32_e32 vcc, 1, v0
	s_cmp_lg_u64 vcc, 0
	s_cselect_b32 s98, 1, 0
	v_writelane_b32 v255, s98, 63
	s_and_b32 s48, s27, 3
	s_ashr_i32 s5, s2, 3
	s_ashr_i32 s33, s33, 3
	s_lshl_b32 s0, s76, 2
	s_add_u32 s0, s74, s0
	s_addc_u32 s1, s75, 0
	v_writelane_b32 v253, s27, 39
	s_add_u32 s0, s0, 0x1ad38500
	v_writelane_b32 v253, s0, 40
	s_addc_u32 s0, s1, 0
	v_writelane_b32 v253, s0, 41
	s_add_u32 s0, s74, 0x13800000
	s_addc_u32 s1, s75, 0
	v_writelane_b32 v253, s0, 42
	s_mul_i32 s94, s48, 6
	v_mov_b32_e32 v1, 0
	v_writelane_b32 v253, s1, 43
	s_lshl_b32 s0, s48, 6
	v_readlane_b32 s4, v253, 0
	s_lshl_b32 s1, s4, 3
	s_or_b32 s95, s1, 16
	s_lshl_b32 s96, s4, 4
	s_add_u32 s36, s74, 0x14400000
	s_addc_u32 s37, s75, 0
	s_add_u32 s66, s3, 0x4200
	s_addc_u32 s67, s86, 0
	s_add_u32 s80, s3, 0x4400
	s_addc_u32 s81, s86, 0
	s_add_u32 s82, s3, 0x4500
	s_addc_u32 s83, s86, 0
	s_add_u32 s6, s3, 0x4600
	v_writelane_b32 v253, s1, 44
	s_addc_u32 s7, s86, 0
	v_writelane_b32 v253, s6, 45
	s_mulk_i32 s48, 0x300
	v_mov_b32_e32 v161, 0x130b0
	v_writelane_b32 v253, s7, 46
	s_add_u32 s6, s3, 0x4700
	s_addc_u32 s7, s86, 0
	v_writelane_b32 v253, s6, 47
	v_mov_b32_e32 v201, 0x3727c5ac
	v_mbcnt_hi_u32_b32 v202, -1, v60
	v_writelane_b32 v253, s7, 48
	s_add_u32 s6, s3, 0x4800
	s_addc_u32 s7, s86, 0
	v_writelane_b32 v253, s6, 49
	v_mov_b32_e32 v205, 0xfffffc00
	v_mov_b32_e32 v206, 0xffffff00
	v_writelane_b32 v253, s7, 50
	s_add_u32 s6, s3, 0x4900
	s_addc_u32 s7, s86, 0
	v_writelane_b32 v253, s6, 51
	v_mov_b32_e32 v207, 0xe00
	v_mov_b32_e32 v208, 0xe40
	v_writelane_b32 v253, s7, 52
	s_add_u32 s6, s3, 0x4a00
	s_addc_u32 s7, s86, 0
	v_writelane_b32 v253, s6, 53
	v_mov_b32_e32 v209, 0xe60
	v_mov_b32_e32 v210, 0x200
	v_writelane_b32 v253, s7, 54
	s_add_u32 s6, s3, 0x4b00
	s_addc_u32 s7, s86, 0
	v_writelane_b32 v253, s6, 55
	v_mov_b32_e32 v211, 0xff800000
	v_mov_b32_e32 v212, 0xff61b1e6
	v_writelane_b32 v253, s7, 56
	s_add_u32 s6, s3, 0x4c00
	s_addc_u32 s7, s86, 0
	v_writelane_b32 v253, s6, 57
	s_movk_i32 s51, 0x300
	s_movk_i32 s52, 0x800
	v_writelane_b32 v253, s7, 58
	s_add_u32 s6, s3, 0x4d00
	s_addc_u32 s7, s86, 0
	v_writelane_b32 v253, s6, 59
	s_movk_i32 s53, 0x90
	s_mov_b32 s54, 0x10000
	v_writelane_b32 v253, s7, 60
	s_add_u32 s6, s3, 0x4e00
	s_addc_u32 s7, s86, 0
	v_writelane_b32 v253, s6, 61
	s_mov_b32 s55, 0x20000
	s_mov_b32 s56, 0x30000
	v_writelane_b32 v253, s7, 62
	s_add_u32 s6, s3, 0x4f00
	s_addc_u32 s7, s86, 0
	v_writelane_b32 v253, s6, 63
	s_movk_i32 s57, 0xfff
	s_movk_i32 s58, 0x1000
	v_writelane_b32 v254, s7, 0
	s_add_u32 s6, s3, 0x5000
	s_addc_u32 s7, s86, 0
	v_writelane_b32 v254, s6, 1
	s_movk_i32 s59, 0x110
	s_movk_i32 s60, 0x81
	v_writelane_b32 v254, s7, 2
	s_add_u32 s6, s3, 0x5100
	s_addc_u32 s7, s86, 0
	v_writelane_b32 v254, s6, 3
	s_mov_b32 s61, 0xff800000
	s_mov_b32 s62, 0x800000
	v_writelane_b32 v254, s7, 4
	s_add_u32 s6, s3, 0x5200
	s_addc_u32 s7, s86, 0
	s_add_u32 s84, s3, 0x5300
	v_writelane_b32 v254, s6, 5
	s_addc_u32 s85, s86, 0
	s_movk_i32 s63, 0x6000
	v_writelane_b32 v254, s7, 6
	s_add_u32 s6, s3, 0x7400
	s_addc_u32 s7, s86, 0
	v_writelane_b32 v254, s6, 7
	s_movk_i32 s64, 0x2ff
	s_movk_i32 s65, 0xff80
	v_writelane_b32 v254, s7, 8
	s_add_u32 s6, s3, 0x7500
	s_addc_u32 s7, s86, 0
	s_bfe_u32 s1, s2, 0x30001
	v_writelane_b32 v254, s6, 9
	s_lshl_b32 s2, s1, 6
	s_add_i32 s1, s87, s1
	v_writelane_b32 v254, s7, 10
	s_add_u32 s6, s74, 0x15c00000
	v_writelane_b32 v254, s1, 11
	s_addc_u32 s7, s75, 0
	v_writelane_b32 v254, s6, 12
	s_add_u32 s1, s74, 0x18688500
	s_mov_b64 s[88:89], 0x100
	v_writelane_b32 v254, s7, 13
	v_writelane_b32 v254, s1, 14
	s_addc_u32 s1, s75, 0
	v_writelane_b32 v254, s1, 15
	s_add_u32 s1, s74, 0x18788500
	v_writelane_b32 v254, s1, 16
	s_addc_u32 s1, s75, 0
	v_writelane_b32 v254, s1, 17
	s_add_u32 s1, s74, 0x18588500
	v_writelane_b32 v254, s1, 18
	s_addc_u32 s1, s75, 0
	v_writelane_b32 v254, s1, 19
	s_add_u32 s1, s74, 0x18608500
	v_writelane_b32 v254, s1, 20
	s_addc_u32 s1, s75, 0
	v_writelane_b32 v254, s1, 21
	s_add_u32 s1, s74, 0x18588000
	v_writelane_b32 v254, s1, 22
	s_addc_u32 s1, s75, 0
	v_writelane_b32 v254, s1, 23
	s_add_u32 s1, s74, 0x1000000
	v_writelane_b32 v254, s1, 24
	s_addc_u32 s1, s75, 0
	s_add_u32 s92, s74, 0x12000000
	s_addc_u32 s93, s75, 0
	s_add_u32 s6, s74, 0x18002000
	v_writelane_b32 v254, s1, 25
	s_addc_u32 s7, s75, 0
	v_writelane_b32 v254, s6, 26
	s_lshl_b32 s49, s4, 10
	s_lshl_b32 s1, s5, 2
	v_writelane_b32 v254, s7, 27
	v_writelane_b32 v254, s5, 28
	s_lshl_b32 s97, s33, 2
	s_bitset1_b32 s49, 11
	s_lshl_b32 s50, s4, 11
	v_writelane_b32 v254, s1, 29
	s_add_u32 s1, s74, 0x1800000
	v_writelane_b32 v254, s1, 30
	s_addc_u32 s1, s75, 0
	s_add_u32 s34, s74, 0x16800000
	s_addc_u32 s35, s75, 0
	s_add_u32 s4, s74, 0x18928700
	v_writelane_b32 v254, s1, 31
	s_addc_u32 s5, s75, 0
	v_writelane_b32 v254, s4, 32
	s_add_u32 s1, s74, 0x18908500
	s_mov_b64 s[22:23], 0
	v_writelane_b32 v254, s5, 33
	v_writelane_b32 v254, s1, 34
	s_addc_u32 s1, s75, 0
	v_writelane_b32 v254, s1, 35
	s_add_u32 s1, s74, 0x2000000
	v_writelane_b32 v254, s1, 36
	s_addc_u32 s1, s75, 0
	v_writelane_b32 v254, s1, 37
	s_add_u32 s1, s74, 0x18888500
	v_writelane_b32 v254, s1, 38
	s_addc_u32 s1, s75, 0
	v_writelane_b32 v254, s1, 39
	s_add_u32 s1, s74, 0x188c8500
	v_writelane_b32 v254, s1, 40
	s_addc_u32 s1, s75, 0
	s_add_u32 s8, s74, 0x30180
	s_addc_u32 s9, s75, 0
	s_add_u32 s10, s74, 0x10180
	s_addc_u32 s11, s75, 0
	s_add_u32 s12, s74, 0x180
	s_addc_u32 s13, s75, 0
	s_add_u32 s26, s74, 0x100
	s_addc_u32 s27, s75, 0
	s_add_u32 s28, s74, 0x10100
	s_addc_u32 s29, s75, 0
	s_add_u32 s30, s74, 0x20100
	v_writelane_b32 v254, s1, 41
	s_addc_u32 s31, s75, 0
	s_lshl_b32 s0, s0, 2
	v_writelane_b32 v254, s0, 42
	s_lshl_b32 s0, s2, 2
	s_mov_b64 s[4:5], s[72:73]
	v_writelane_b32 v254, s0, 43
	s_mov_b64 s[6:7], s[74:75]
	v_writelane_b32 v254, s0, 44
	s_mov_b32 s86, 0x3fd744fd
	s_mov_b32 s18, s21
	v_writelane_b32 v254, s1, 45
	v_writelane_b32 v254, s2, 46
	v_writelane_b32 v254, s3, 47
	v_writelane_b32 v254, s4, 48
	v_writelane_b32 v254, s5, 49
	v_writelane_b32 v254, s6, 50
	v_writelane_b32 v254, s7, 51
	v_writelane_b32 v254, s66, 52
	s_nop 1
	v_writelane_b32 v254, s67, 53
	v_writelane_b32 v254, s80, 54
	s_nop 1
	v_writelane_b32 v254, s81, 55
	v_writelane_b32 v254, s82, 56
	s_nop 1
	v_writelane_b32 v254, s83, 57
	v_writelane_b32 v254, s34, 58
	s_nop 1
	v_writelane_b32 v254, s35, 59
	s_branch .LBB0_295

.LBB0_548:
	s_mul_i32 s0, s20, 0x2400
	v_mov_b32_e32 v12, v7
	v_add_u32_e32 v7, s0, v173
	v_mov_b32_e32 v176, v8
	ds_read_b128 v[16:19], v7
	ds_read_b128 v[20:23], v7 offset:32
	ds_read_b128 v[24:27], v7 offset:64
	ds_read_b128 v[28:31], v7 offset:96
	ds_read_b128 v[32:35], v7 offset:4608
	ds_read_b128 v[36:39], v7 offset:4640
	ds_read_b128 v[40:43], v7 offset:4672
	ds_read_b128 v[44:47], v7 offset:4704
	s_waitcnt lgkmcnt(7)
	v_mfma_f32_32x32x16_bf16 v[96:111], v[16:19], v[112:115], 0
	s_waitcnt lgkmcnt(6)
	v_mfma_f32_32x32x16_bf16 v[96:111], v[20:23], v[116:119], v[96:111]
	s_waitcnt lgkmcnt(5)
	v_mfma_f32_32x32x16_bf16 v[96:111], v[24:27], v[120:123], v[96:111]
	s_waitcnt lgkmcnt(4)
	v_mfma_f32_32x32x16_bf16 v[96:111], v[28:31], v[124:127], v[96:111]
	s_waitcnt lgkmcnt(3)
	v_mfma_f32_32x32x16_bf16 v[80:95], v[32:35], v[112:115], 0
	s_waitcnt lgkmcnt(2)
	v_mfma_f32_32x32x16_bf16 v[80:95], v[36:39], v[116:119], v[80:95]
	s_waitcnt lgkmcnt(1)
	v_mfma_f32_32x32x16_bf16 v[80:95], v[40:43], v[120:123], v[80:95]
	s_waitcnt lgkmcnt(0)
	v_mfma_f32_32x32x16_bf16 v[80:95], v[44:47], v[124:127], v[80:95]
	v_lshl_add_u32 v2, s20, 7, v174
	v_add_u32_e32 v4, 0x6800, v2
	v_add_u32_e32 v2, 0x4800, v2
	ds_read2_b64 v[16:19], v2 offset1:2
	ds_read2_b64 v[20:23], v4 offset0:64 offset1:66
	ds_read2_b64 v[24:27], v2 offset0:4 offset1:6
	ds_read2_b64 v[28:31], v4 offset0:68 offset1:70
	ds_read2_b64 v[32:35], v2 offset0:8 offset1:10
	ds_read2_b64 v[36:39], v4 offset0:72 offset1:74
	ds_read2_b64 v[40:43], v2 offset0:12 offset1:14
	ds_read2_b64 v[44:47], v4 offset0:76 offset1:78
	s_cmp_lg_u64 s[4:5], 0
	s_cbranch_scc0 .Lbattn_plain
	v_lshl_add_u32 v2, s20, 6, v0
	v_sub_u32_e32 v4, 0, v2
	v_add_u32_e32 v5, 1, v2
	v_not_b32_e32 v7, v2
	v_max_i32_e32 v4, v2, v4
	v_max_i32_e32 v5, v5, v7
	v_cmp_gt_u32_e32 vcc, s60, v4
	v_mul_f32_e32 v4, s9, v97
	v_cmp_gt_u32_e64 s[0:1], s60, v5
	v_add_u32_e32 v7, 2, v2
	v_sub_u32_e32 v8, -2, v2
	v_cndmask_b32_e64 v5, v211, v4, s[0:1]
	v_max_i32_e32 v7, v7, v8
	v_cndmask_b32_e64 v4, v4, v5, s[4:5]
	v_mul_f32_e32 v5, s9, v98
	v_cmp_gt_u32_e64 s[0:1], s60, v7
	v_add_u32_e32 v8, 3, v2
	v_sub_u32_e32 v9, -3, v2
	v_cndmask_b32_e64 v7, v211, v5, s[0:1]
	v_max_i32_e32 v8, v8, v9
	v_cndmask_b32_e64 v5, v5, v7, s[4:5]
	v_mul_f32_e32 v7, s9, v99
	v_cmp_gt_u32_e64 s[0:1], s60, v8
	v_add_u32_e32 v9, 8, v2
	v_sub_u32_e32 v10, -8, v2
	v_cndmask_b32_e64 v8, v211, v7, s[0:1]
	v_max_i32_e32 v9, v9, v10
	v_cndmask_b32_e64 v8, v7, v8, s[4:5]
	v_mul_f32_e32 v7, s9, v100
	v_cmp_gt_u32_e64 s[0:1], s60, v9
	v_add_u32_e32 v10, 9, v2
	v_sub_u32_e32 v11, -9, v2
	v_cndmask_b32_e64 v9, v211, v7, s[0:1]
	v_max_i32_e32 v10, v10, v11
	v_cndmask_b32_e64 v9, v7, v9, s[4:5]
	v_mul_f32_e32 v7, s9, v101
	v_cmp_gt_u32_e64 s[0:1], s60, v10
	v_add_u32_e32 v11, 10, v2
	v_sub_u32_e32 v13, -10, v2
	v_cndmask_b32_e64 v10, v211, v7, s[0:1]
	v_max_i32_e32 v11, v11, v13
	v_cndmask_b32_e64 v10, v7, v10, s[4:5]
	v_mul_f32_e32 v7, s9, v102
	v_cmp_gt_u32_e64 s[0:1], s60, v11
	v_add_u32_e32 v13, 11, v2
	v_sub_u32_e32 v14, -11, v2
	v_cndmask_b32_e64 v11, v211, v7, s[0:1]
	v_max_i32_e32 v13, v13, v14
	v_cndmask_b32_e64 v11, v7, v11, s[4:5]
	v_mul_f32_e32 v7, s9, v103
	v_cmp_gt_u32_e64 s[0:1], s60, v13
	v_add_u32_e32 v14, 16, v2
	v_sub_u32_e32 v15, -16, v2
	v_cndmask_b32_e64 v13, v211, v7, s[0:1]
	v_max_i32_e32 v14, v14, v15
	v_mul_f32_e32 v3, s9, v96
	v_cndmask_b32_e64 v13, v7, v13, s[4:5]
	v_mul_f32_e32 v7, s9, v104
	v_cmp_gt_u32_e64 s[0:1], s60, v14
	v_add_u32_e32 v15, 17, v2
	v_sub_u32_e32 v96, 0xffffffef, v2
	v_cndmask_b32_e64 v14, v211, v7, s[0:1]
	v_max_i32_e32 v15, v15, v96
	v_cndmask_b32_e64 v14, v7, v14, s[4:5]
	v_mul_f32_e32 v7, s9, v105
	v_cmp_gt_u32_e64 s[0:1], s60, v15
	v_add_u32_e32 v96, 18, v2
	v_sub_u32_e32 v97, 0xffffffee, v2
	v_cndmask_b32_e64 v15, v211, v7, s[0:1]
	v_max_i32_e32 v96, v96, v97
	v_cndmask_b32_e64 v15, v7, v15, s[4:5]
	v_mul_f32_e32 v7, s9, v106
	v_cmp_gt_u32_e64 s[0:1], s60, v96
	v_add_u32_e32 v97, 19, v2
	v_sub_u32_e32 v98, 0xffffffed, v2
	v_cndmask_b32_e64 v96, v211, v7, s[0:1]
	v_max_i32_e32 v97, v97, v98
	v_cndmask_b32_e64 v96, v7, v96, s[4:5]
	v_mul_f32_e32 v7, s9, v107
	v_cmp_gt_u32_e64 s[0:1], s60, v97
	v_add_u32_e32 v98, 24, v2
	v_sub_u32_e32 v99, 0xffffffe8, v2
	v_cndmask_b32_e64 v97, v211, v7, s[0:1]
	v_max_i32_e32 v98, v98, v99
	v_cndmask_b32_e64 v97, v7, v97, s[4:5]
	v_mul_f32_e32 v7, s9, v108
	v_cmp_gt_u32_e64 s[0:1], s60, v98
	v_add_u32_e32 v99, 25, v2
	v_sub_u32_e32 v100, 0xffffffe7, v2
	v_cndmask_b32_e64 v98, v211, v7, s[0:1]
	v_max_i32_e32 v99, v99, v100
	v_cndmask_b32_e64 v98, v7, v98, s[4:5]
	v_mul_f32_e32 v7, s9, v109
	v_cmp_gt_u32_e64 s[0:1], s60, v99
	v_add_u32_e32 v100, 26, v2
	v_sub_u32_e32 v101, 0xffffffe6, v2
	v_cndmask_b32_e64 v99, v211, v7, s[0:1]
	v_max_i32_e32 v100, v100, v101
	v_cndmask_b32_e64 v99, v7, v99, s[4:5]
	v_mul_f32_e32 v7, s9, v110
	v_cmp_gt_u32_e64 s[0:1], s60, v100
	v_add_u32_e32 v101, 27, v2
	v_sub_u32_e32 v102, 0xffffffe5, v2
	v_cndmask_b32_e64 v100, v211, v7, s[0:1]
	v_max_i32_e32 v101, v101, v102
	v_cndmask_b32_e64 v100, v7, v100, s[4:5]
	v_mul_f32_e32 v7, s9, v111
	v_cmp_gt_u32_e64 s[0:1], s60, v101
	v_sub_u32_e32 v102, 0xffffffe0, v2
	s_nop 0
	v_cndmask_b32_e64 v101, v211, v7, s[0:1]
	v_cndmask_b32_e64 v101, v7, v101, s[4:5]
	v_mul_f32_e32 v7, s9, v80
	v_add_u32_e32 v80, 32, v2
	v_max_i32_e32 v80, v80, v102
	v_cmp_gt_u32_e64 s[0:1], s60, v80
	v_sub_u32_e32 v102, 0xffffffdf, v2
	s_nop 0
	v_cndmask_b32_e64 v80, v211, v7, s[0:1]
	v_cndmask_b32_e64 v80, v7, v80, s[4:5]
	v_mul_f32_e32 v7, s9, v81
	v_add_u32_e32 v81, 33, v2
	v_max_i32_e32 v81, v81, v102
	v_cmp_gt_u32_e64 s[0:1], s60, v81
	s_nop 1
	v_cndmask_b32_e64 v81, v211, v7, s[0:1]
	v_cndmask_b32_e64 v102, v7, v81, s[4:5]
	v_mul_f32_e32 v7, s9, v82
	v_add_u32_e32 v81, 34, v2
	v_sub_u32_e32 v82, 0xffffffde, v2
	v_max_i32_e32 v81, v81, v82
	v_cmp_gt_u32_e64 s[0:1], s60, v81
	v_sub_u32_e32 v82, 0xffffffdd, v2
	s_nop 0
	v_cndmask_b32_e64 v81, v211, v7, s[0:1]
	v_cndmask_b32_e64 v103, v7, v81, s[4:5]
	v_add_u32_e32 v81, 35, v2
	v_max_i32_e32 v81, v81, v82
	v_mul_f32_e32 v7, s9, v83
	v_cmp_gt_u32_e64 s[0:1], s60, v81
	v_sub_u32_e32 v82, 0xffffffd8, v2
	s_nop 0
	v_cndmask_b32_e64 v81, v211, v7, s[0:1]
	v_cndmask_b32_e64 v104, v7, v81, s[4:5]
	v_add_u32_e32 v81, 40, v2
	v_max_i32_e32 v81, v81, v82
	v_mul_f32_e32 v7, s9, v84
	v_cmp_gt_u32_e64 s[0:1], s60, v81
	v_sub_u32_e32 v82, 0xffffffd7, v2
	s_nop 0
	v_cndmask_b32_e64 v81, v211, v7, s[0:1]
	v_cndmask_b32_e64 v105, v7, v81, s[4:5]
	v_add_u32_e32 v81, 41, v2
	v_max_i32_e32 v81, v81, v82
	v_mul_f32_e32 v7, s9, v85
	v_cmp_gt_u32_e64 s[0:1], s60, v81
	v_sub_u32_e32 v82, 0xffffffd6, v2
	s_nop 0
	v_cndmask_b32_e64 v81, v211, v7, s[0:1]
	v_cndmask_b32_e64 v106, v7, v81, s[4:5]
	v_add_u32_e32 v81, 42, v2
	v_max_i32_e32 v81, v81, v82
	v_mul_f32_e32 v7, s9, v86
	v_cmp_gt_u32_e64 s[0:1], s60, v81
	v_sub_u32_e32 v82, 0xffffffd5, v2
	s_nop 0
	v_cndmask_b32_e64 v81, v211, v7, s[0:1]
	v_cndmask_b32_e64 v107, v7, v81, s[4:5]
	v_add_u32_e32 v81, 43, v2
	v_max_i32_e32 v81, v81, v82
	v_mul_f32_e32 v7, s9, v87
	v_cmp_gt_u32_e64 s[0:1], s60, v81
	v_sub_u32_e32 v82, 0xffffffd0, v2
	s_nop 0
	v_cndmask_b32_e64 v81, v211, v7, s[0:1]
	v_cndmask_b32_e64 v108, v7, v81, s[4:5]
	v_add_u32_e32 v81, 48, v2
	v_max_i32_e32 v81, v81, v82
	v_mul_f32_e32 v7, s9, v88
	v_cmp_gt_u32_e64 s[0:1], s60, v81
	v_sub_u32_e32 v82, 0xffffffcf, v2
	s_nop 0
	v_cndmask_b32_e64 v81, v211, v7, s[0:1]
	v_cndmask_b32_e64 v88, v7, v81, s[4:5]
	v_add_u32_e32 v81, 49, v2
	v_max_i32_e32 v81, v81, v82
	v_mul_f32_e32 v7, s9, v89
	v_cmp_gt_u32_e64 s[0:1], s60, v81
	v_sub_u32_e32 v82, 0xffffffce, v2
	s_nop 0
	v_cndmask_b32_e64 v81, v211, v7, s[0:1]
	v_cndmask_b32_e64 v109, v7, v81, s[4:5]
	v_add_u32_e32 v81, 50, v2
	v_max_i32_e32 v81, v81, v82
	v_mul_f32_e32 v7, s9, v90
	v_cmp_gt_u32_e64 s[0:1], s60, v81
	v_sub_u32_e32 v82, 0xffffffcd, v2
	s_nop 0
	v_cndmask_b32_e64 v81, v211, v7, s[0:1]
	v_cndmask_b32_e64 v110, v7, v81, s[4:5]
	v_add_u32_e32 v81, 51, v2
	v_max_i32_e32 v81, v81, v82
	v_mul_f32_e32 v7, s9, v91
	v_cmp_gt_u32_e64 s[0:1], s60, v81
	v_sub_u32_e32 v82, 0xffffffc8, v2
	s_nop 0
	v_cndmask_b32_e64 v81, v211, v7, s[0:1]
	v_cndmask_b32_e64 v111, v7, v81, s[4:5]
	v_add_u32_e32 v81, 56, v2
	v_max_i32_e32 v81, v81, v82
	v_mul_f32_e32 v7, s9, v92
	v_cmp_gt_u32_e64 s[0:1], s60, v81
	v_sub_u32_e32 v82, 0xffffffc7, v2
	s_nop 0
	v_cndmask_b32_e64 v81, v211, v7, s[0:1]
	v_cndmask_b32_e64 v177, v7, v81, s[4:5]
	v_add_u32_e32 v81, 57, v2
	v_max_i32_e32 v81, v81, v82
	v_mul_f32_e32 v7, s9, v93
	v_cmp_gt_u32_e64 s[0:1], s60, v81
	v_sub_u32_e32 v82, 0xffffffc6, v2
	s_nop 0
	v_cndmask_b32_e64 v81, v211, v7, s[0:1]
	v_cndmask_b32_e64 v178, v7, v81, s[4:5]
	v_add_u32_e32 v81, 58, v2
	v_max_i32_e32 v81, v81, v82
	v_mul_f32_e32 v7, s9, v94
	v_cmp_gt_u32_e64 s[0:1], s60, v81
	s_nop 1
	v_cndmask_b32_e64 v81, v211, v7, s[0:1]
	v_cndmask_b32_e64 v179, v7, v81, s[4:5]
	v_add_u32_e32 v81, 59, v2
	v_sub_u32_e32 v2, 0xffffffc5, v2
	v_max_i32_e32 v2, v81, v2
	v_mul_f32_e32 v7, s9, v95
	v_cmp_gt_u32_e64 s[0:1], s60, v2
	v_cndmask_b32_e32 v81, v211, v3, vcc
	v_cndmask_b32_e64 v3, v3, v81, s[4:5]
	v_cndmask_b32_e64 v2, v211, v7, s[0:1]
	v_cndmask_b32_e64 v2, v7, v2, s[4:5]
	s_branch .Lbattn_scored
.Lbattn_plain:
	v_mul_f32_e32 v3, s9, v96
	v_mul_f32_e32 v4, s9, v97
	v_mul_f32_e32 v5, s9, v98
	v_mul_f32_e32 v8, s9, v99
	v_mul_f32_e32 v9, s9, v100
	v_mul_f32_e32 v10, s9, v101
	v_mul_f32_e32 v11, s9, v102
	v_mul_f32_e32 v13, s9, v103
	v_mul_f32_e32 v14, s9, v104
	v_mul_f32_e32 v15, s9, v105
	v_mul_f32_e32 v96, s9, v106
	v_mul_f32_e32 v97, s9, v107
	v_mul_f32_e32 v98, s9, v108
	v_mul_f32_e32 v99, s9, v109
	v_mul_f32_e32 v100, s9, v110
	v_mul_f32_e32 v101, s9, v111
	v_mul_f32_e32 v80, s9, v80
	v_mul_f32_e32 v102, s9, v81
	v_mul_f32_e32 v103, s9, v82
	v_mul_f32_e32 v104, s9, v83
	v_mul_f32_e32 v105, s9, v84
	v_mul_f32_e32 v106, s9, v85
	v_mul_f32_e32 v107, s9, v86
	v_mul_f32_e32 v108, s9, v87
	v_mul_f32_e32 v88, s9, v88
	v_mul_f32_e32 v109, s9, v89
	v_mul_f32_e32 v110, s9, v90
	v_mul_f32_e32 v111, s9, v91
	v_mul_f32_e32 v177, s9, v92
	v_mul_f32_e32 v178, s9, v93
	v_mul_f32_e32 v179, s9, v94
	v_mul_f32_e32 v2, s9, v95
.Lbattn_scored:
	v_max3_f32 v7, v3, s61, v4
	v_max3_f32 v7, v7, v5, v8
	v_max3_f32 v7, v7, v9, v10
	v_max3_f32 v7, v7, v11, v13
	v_max3_f32 v7, v7, v14, v15
	v_max3_f32 v7, v7, v96, v97
	v_max3_f32 v7, v7, v98, v99
	v_max3_f32 v7, v7, v100, v101
	v_max3_f32 v7, v7, v80, v102
	v_max3_f32 v7, v7, v103, v104
	v_max3_f32 v7, v7, v105, v106
	v_max3_f32 v7, v7, v107, v108
	v_max3_f32 v7, v7, v88, v109
	v_max3_f32 v7, v7, v110, v111
	v_max3_f32 v7, v7, v177, v178
	v_max3_f32 v7, v7, v179, v2
	ds_bpermute_b32 v81, v6, v7
	s_waitcnt lgkmcnt(0)
	v_max3_f32 v7, v12, v7, v81
	v_cmp_eq_f32_e32 vcc, s61, v7
	v_sub_f32_e32 v180, v12, v7
	s_nop 0
	v_cndmask_b32_e64 v181, v7, 0, vcc
	v_exp_f32_e32 v180, v180
	v_sub_f32_e32 v3, v3, v181
	v_cndmask_b32_e64 v180, v180, 1.0, vcc
	v_pk_mul_f32 v[62:63], v[62:63], v[180:181] op_sel_hi:[1,0]
	v_pk_mul_f32 v[60:61], v[60:61], v[180:181] op_sel_hi:[1,0]
	v_pk_mul_f32 v[58:59], v[58:59], v[180:181] op_sel_hi:[1,0]
	v_pk_mul_f32 v[56:57], v[56:57], v[180:181] op_sel_hi:[1,0]
	v_pk_mul_f32 v[54:55], v[54:55], v[180:181] op_sel_hi:[1,0]
	v_pk_mul_f32 v[52:53], v[52:53], v[180:181] op_sel_hi:[1,0]
	v_pk_mul_f32 v[50:51], v[50:51], v[180:181] op_sel_hi:[1,0]
	v_pk_mul_f32 v[48:49], v[48:49], v[180:181] op_sel_hi:[1,0]
	v_pk_mul_f32 v[78:79], v[78:79], v[180:181] op_sel_hi:[1,0]
	v_pk_mul_f32 v[76:77], v[76:77], v[180:181] op_sel_hi:[1,0]
	v_pk_mul_f32 v[74:75], v[74:75], v[180:181] op_sel_hi:[1,0]
	v_pk_mul_f32 v[72:73], v[72:73], v[180:181] op_sel_hi:[1,0]
	v_pk_mul_f32 v[70:71], v[70:71], v[180:181] op_sel_hi:[1,0]
	v_pk_mul_f32 v[68:69], v[68:69], v[180:181] op_sel_hi:[1,0]
	v_pk_mul_f32 v[66:67], v[66:67], v[180:181] op_sel_hi:[1,0]
	v_pk_mul_f32 v[64:65], v[64:65], v[180:181] op_sel_hi:[1,0]
	v_exp_f32_e32 v3, v3
	v_sub_f32_e32 v4, v4, v181
	v_exp_f32_e32 v4, v4
	v_sub_f32_e32 v5, v5, v181
	v_exp_f32_e32 v5, v5
	v_sub_f32_e32 v8, v8, v181
	v_exp_f32_e32 v182, v8
	v_sub_f32_e32 v9, v9, v181
	v_add_f32_e32 v12, 0, v3
	v_exp_f32_e32 v183, v9
	v_sub_f32_e32 v9, v10, v181
	v_add_f32_e32 v12, v4, v12
	v_exp_f32_e32 v184, v9
	v_sub_f32_e32 v9, v11, v181
	v_add_f32_e32 v12, v5, v12
	v_exp_f32_e32 v185, v9
	v_sub_f32_e32 v9, v13, v181
	v_add_f32_e32 v8, v182, v12
	v_exp_f32_e32 v186, v9
	v_sub_f32_e32 v9, v14, v181
	v_add_f32_e32 v8, v183, v8
	v_cvt_pk_bf16_f32 v236, v3, v4
	v_cvt_pk_bf16_f32 v237, v5, v182
	v_cvt_pk_bf16_f32 v238, v183, v184
	v_cvt_pk_bf16_f32 v239, v185, v186
	s_nop 1
	v_mfma_f32_32x32x16_bf16 v[48:63], v[16:19], v[236:239], v[48:63]
	v_mfma_f32_32x32x16_bf16 v[64:79], v[20:23], v[236:239], v[64:79]
	v_exp_f32_e32 v9, v9
	v_sub_f32_e32 v10, v15, v181
	v_add_f32_e32 v8, v184, v8
	v_exp_f32_e32 v10, v10
	v_sub_f32_e32 v11, v96, v181
	v_add_f32_e32 v8, v185, v8
	v_exp_f32_e32 v11, v11
	v_sub_f32_e32 v12, v97, v181
	v_add_f32_e32 v8, v186, v8
	v_exp_f32_e32 v12, v12
	v_sub_f32_e32 v13, v98, v181
	v_add_f32_e32 v8, v9, v8
	v_exp_f32_e32 v13, v13
	v_sub_f32_e32 v14, v99, v181
	v_add_f32_e32 v8, v10, v8
	v_exp_f32_e32 v14, v14
	v_sub_f32_e32 v15, v100, v181
	v_add_f32_e32 v8, v11, v8
	v_exp_f32_e32 v15, v15
	v_sub_f32_e32 v81, v101, v181
	v_add_f32_e32 v8, v12, v8
	v_exp_f32_e32 v81, v81
	v_sub_f32_e32 v80, v80, v181
	v_add_f32_e32 v8, v13, v8
	v_cvt_pk_bf16_f32 v236, v9, v10
	v_cvt_pk_bf16_f32 v237, v11, v12
	v_cvt_pk_bf16_f32 v238, v13, v14
	v_cvt_pk_bf16_f32 v239, v15, v81
	s_nop 1
	v_mfma_f32_32x32x16_bf16 v[48:63], v[24:27], v[236:239], v[48:63]
	v_mfma_f32_32x32x16_bf16 v[64:79], v[28:31], v[236:239], v[64:79]
	v_exp_f32_e32 v80, v80
	v_sub_f32_e32 v82, v102, v181
	v_add_f32_e32 v8, v14, v8
	v_exp_f32_e32 v82, v82
	v_sub_f32_e32 v83, v103, v181
	v_add_f32_e32 v8, v15, v8
	v_exp_f32_e32 v83, v83
	v_sub_f32_e32 v84, v104, v181
	v_add_f32_e32 v8, v81, v8
	v_exp_f32_e32 v84, v84
	v_sub_f32_e32 v85, v105, v181
	v_add_f32_e32 v8, v80, v8
	v_exp_f32_e32 v85, v85
	v_sub_f32_e32 v86, v106, v181
	v_add_f32_e32 v8, v82, v8
	v_exp_f32_e32 v86, v86
	v_sub_f32_e32 v87, v107, v181
	v_add_f32_e32 v8, v83, v8
	v_exp_f32_e32 v87, v87
	v_sub_f32_e32 v89, v108, v181
	v_add_f32_e32 v8, v84, v8
	v_exp_f32_e32 v89, v89
	v_sub_f32_e32 v88, v88, v181
	v_add_f32_e32 v8, v85, v8
	v_cvt_pk_bf16_f32 v236, v80, v82
	v_cvt_pk_bf16_f32 v237, v83, v84
	v_cvt_pk_bf16_f32 v238, v85, v86
	v_cvt_pk_bf16_f32 v239, v87, v89
	s_nop 1
	v_mfma_f32_32x32x16_bf16 v[48:63], v[32:35], v[236:239], v[48:63]
	v_mfma_f32_32x32x16_bf16 v[64:79], v[36:39], v[236:239], v[64:79]
	v_exp_f32_e32 v88, v88
	v_sub_f32_e32 v90, v109, v181
	v_add_f32_e32 v8, v86, v8
	v_exp_f32_e32 v90, v90
	v_sub_f32_e32 v91, v110, v181
	v_add_f32_e32 v8, v87, v8
	v_exp_f32_e32 v91, v91
	v_sub_f32_e32 v92, v111, v181
	v_add_f32_e32 v8, v89, v8
	v_exp_f32_e32 v92, v92
	v_sub_f32_e32 v93, v177, v181
	v_add_f32_e32 v8, v88, v8
	v_exp_f32_e32 v93, v93
	v_sub_f32_e32 v94, v178, v181
	v_add_f32_e32 v8, v90, v8
	v_exp_f32_e32 v94, v94
	v_sub_f32_e32 v95, v179, v181
	v_add_f32_e32 v8, v91, v8
	v_exp_f32_e32 v95, v95
	v_sub_f32_e32 v2, v2, v181
	v_add_f32_e32 v8, v92, v8
	v_exp_f32_e32 v96, v2
	v_add_f32_e32 v8, v93, v8
	v_add_f32_e32 v8, v94, v8
	v_add_f32_e32 v8, v95, v8
	v_add_f32_e32 v8, v96, v8
	v_cvt_pk_bf16_f32 v236, v88, v90
	v_cvt_pk_bf16_f32 v237, v91, v92
	v_cvt_pk_bf16_f32 v238, v93, v94
	v_cvt_pk_bf16_f32 v239, v95, v96
	v_fmac_f32_e32 v8, v176, v180
	s_and_b64 vcc, exec, s[6:7]
	s_mov_b64 s[6:7], 0
	s_mov_b32 s20, 1
	v_mfma_f32_32x32x16_bf16 v[48:63], v[40:43], v[236:239], v[48:63]
	v_mfma_f32_32x32x16_bf16 v[64:79], v[44:47], v[236:239], v[64:79]
	s_cbranch_vccnz .LBB0_548
	s_mov_b64 s[0:1], 0

.LBB0_674:
	s_andn2_saveexec_b64 s[6:7], s[6:7]
	s_cbranch_execz .LBB0_694
	s_mov_b64 s[6:7], exec
	v_readlane_b32 s98, v255, 63
	s_nop 0
	s_cmp_eq_u32 s98, 0
	s_cbranch_scc1 .Lbar_local_g2
	buffer_wbl2 sc1
	s_waitcnt lgkmcnt(0)
	s_waitcnt vmcnt(0)
	v_mbcnt_lo_u32_b32 v0, s6, 0
	v_mbcnt_hi_u32_b32 v0, s7, v0
	v_cmp_eq_u32_e32 vcc, 0, v0
	s_and_saveexec_b64 s[8:9], vcc
	s_cbranch_execz .LBB0_677
	s_bcnt1_i32_b64 s6, s[6:7]
	v_mov_b32_e32 v3, s6
	v_readlane_b32 s6, v254, 7
	v_readlane_b32 s7, v254, 8
	s_nop 4
	global_atomic_add v3, v1, v3, s[6:7] sc0

.Lbar_local_g2:
	s_mov_b64 s[6:7], exec
	v_mbcnt_lo_u32_b32 v0, s6, 0
	v_mbcnt_hi_u32_b32 v0, s7, v0
	v_cmp_eq_u32_e32 vcc, 0, v0
	s_waitcnt vmcnt(0)
	buffer_inv sc1
	s_and_saveexec_b64 s[8:9], vcc
	s_cbranch_execz .LBB0_693
	s_bcnt1_i32_b64 s6, s[6:7]
	v_mov_b32_e32 v0, s6
	v_mov_b32_e32 v2, 0x2000
	global_atomic_add v2, v0, s[4:5] offset:1024

.LBB0_908:
	s_andn2_saveexec_b64 s[4:5], s[4:5]
	s_cbranch_execz .LBB0_293
	s_mov_b64 s[4:5], exec
	v_readlane_b32 s98, v255, 63
	s_nop 0
	s_cmp_eq_u32 s98, 0
	s_cbranch_scc1 .Lbar_local_peer
	buffer_wbl2 sc1
	s_waitcnt lgkmcnt(0)
	s_waitcnt vmcnt(0)
	v_mbcnt_lo_u32_b32 v0, s4, 0
	v_mbcnt_hi_u32_b32 v0, s5, v0
	v_cmp_eq_u32_e32 vcc, 0, v0
	s_and_saveexec_b64 s[6:7], vcc
	s_cbranch_execz .LBB0_911
	s_bcnt1_i32_b64 s4, s[4:5]
	v_mov_b32_e32 v3, s4
	v_readlane_b32 s4, v254, 7
	v_readlane_b32 s5, v254, 8
	s_nop 4
	global_atomic_add v3, v1, v3, s[4:5] sc0

.Lbar_local_peer:
	s_mov_b64 s[4:5], exec
	v_mbcnt_lo_u32_b32 v0, s4, 0
	v_mbcnt_hi_u32_b32 v0, s5, v0
	v_cmp_eq_u32_e32 vcc, 0, v0
	s_waitcnt vmcnt(0)
	buffer_inv sc1
	s_and_saveexec_b64 s[6:7], vcc
	s_cbranch_execz .LBB0_292
	s_bcnt1_i32_b64 s4, s[4:5]
	v_mov_b32_e32 v0, s4
	v_mov_b32_e32 v2, 0x2000
	global_atomic_add v2, v0, s[2:3] offset:1024
	s_branch .LBB0_292
